# compress MLP second stage: all 32 W2 fragment loads issued up front with a single wait, the 16 MFMAs back to back (was 11 serial load-wait-MFMA round trips)
# baseline (speedup 1.0000x reference)
.LBB0_310:
	s_mul_i32 s6, s18, 0x4900
	s_add_i32 s6, s6, 0
	v_lshl_add_u32 v0, v139, 2, s6
	s_cmp_eq_u32 s24, 0
	ds_write2st64_b32 v0, v30, v31 offset1:1
	ds_write2st64_b32 v0, v32, v33 offset0:2 offset1:3
	ds_write2st64_b32 v0, v26, v27 offset0:4 offset1:5
	ds_write2st64_b32 v0, v28, v29 offset0:6 offset1:7
	ds_write2st64_b32 v0, v22, v23 offset0:8 offset1:9
	ds_write2st64_b32 v0, v24, v25 offset0:10 offset1:11
	ds_write2st64_b32 v0, v18, v19 offset0:12 offset1:13
	ds_write2st64_b32 v0, v20, v21 offset0:14 offset1:15
	ds_write2st64_b32 v0, v14, v15 offset0:16 offset1:17
	ds_write2st64_b32 v0, v16, v17 offset0:18 offset1:19
	ds_write2st64_b32 v0, v10, v11 offset0:20 offset1:21
	ds_write2st64_b32 v0, v12, v13 offset0:22 offset1:23
	ds_write2st64_b32 v0, v6, v7 offset0:24 offset1:25
	ds_write2st64_b32 v0, v8, v9 offset0:26 offset1:27
	ds_write2st64_b32 v0, v2, v3 offset0:28 offset1:29
	ds_write2st64_b32 v0, v4, v5 offset0:30 offset1:31
	s_waitcnt lgkmcnt(0)
	s_barrier
	s_cbranch_scc0 .LBB0_327
	v_lshlrev_b32_e32 v34, 2, v138
	v_lshl_add_u64 v[42:43], s[14:15], 2, v[46:47]
	v_ashrrev_i32_e32 v35, 31, v34
	v_lshl_add_u64 v[142:143], v[34:35], 2, v[42:43]
	s_mov_b64 s[6:7], 0x2188000
	ds_read2st64_b32 v[130:131], v0 offset0:73 offset1:74
	ds_read2st64_b32 v[122:123], v0 offset0:75 offset1:76
	ds_read2st64_b32 v[118:119], v0 offset0:77 offset1:78
	ds_read2st64_b32 v[110:111], v0 offset0:79 offset1:80
	ds_read2st64_b32 v[106:107], v0 offset0:81 offset1:82
	ds_read2st64_b32 v[98:99], v0 offset0:83 offset1:84
	ds_read2st64_b32 v[92:93], v0 offset0:85 offset1:86
	ds_read2st64_b32 v[86:87], v0 offset0:87 offset1:88
	ds_read2st64_b32 v[80:81], v0 offset0:89 offset1:90
	ds_read2st64_b32 v[74:75], v0 offset0:91 offset1:92
	ds_read2st64_b32 v[68:69], v0 offset0:93 offset1:94
	ds_read2st64_b32 v[62:63], v0 offset0:95 offset1:96
	ds_read2st64_b32 v[56:57], v0 offset0:97 offset1:98
	ds_read2st64_b32 v[50:51], v0 offset0:99 offset1:100
	ds_read2st64_b32 v[44:45], v0 offset0:101 offset1:102
	ds_read2st64_b32 v[36:37], v0 offset0:103 offset1:104
	ds_read2st64_b32 v[132:133], v0 offset0:146 offset1:147
	ds_read2st64_b32 v[126:127], v0 offset0:148 offset1:149
	ds_read2st64_b32 v[120:121], v0 offset0:150 offset1:151
	ds_read2st64_b32 v[114:115], v0 offset0:152 offset1:153
	ds_read2st64_b32 v[108:109], v0 offset0:154 offset1:155
	ds_read2st64_b32 v[102:103], v0 offset0:156 offset1:157
	ds_read2st64_b32 v[96:97], v0 offset0:158 offset1:159
	ds_read2st64_b32 v[90:91], v0 offset0:160 offset1:161
	ds_read2st64_b32 v[84:85], v0 offset0:162 offset1:163
	ds_read2st64_b32 v[78:79], v0 offset0:164 offset1:165
	ds_read2st64_b32 v[72:73], v0 offset0:166 offset1:167
	ds_read2st64_b32 v[66:67], v0 offset0:168 offset1:169
	ds_read2st64_b32 v[60:61], v0 offset0:170 offset1:171
	ds_read2st64_b32 v[54:55], v0 offset0:172 offset1:173
	ds_read2st64_b32 v[48:49], v0 offset0:174 offset1:175
	ds_read2st64_b32 v[38:39], v0 offset0:176 offset1:177
	ds_read2st64_b32 v[134:135], v0 offset0:219 offset1:220
	ds_read2st64_b32 v[128:129], v0 offset0:221 offset1:222
	ds_read2st64_b32 v[124:125], v0 offset0:223 offset1:224
	ds_read2st64_b32 v[116:117], v0 offset0:225 offset1:226
	ds_read2st64_b32 v[112:113], v0 offset0:227 offset1:228
	ds_read2st64_b32 v[104:105], v0 offset0:229 offset1:230
	ds_read2st64_b32 v[100:101], v0 offset0:231 offset1:232
	ds_read2st64_b32 v[94:95], v0 offset0:233 offset1:234
	ds_read2st64_b32 v[88:89], v0 offset0:235 offset1:236
	ds_read2st64_b32 v[82:83], v0 offset0:237 offset1:238
	ds_read2st64_b32 v[76:77], v0 offset0:239 offset1:240
	ds_read2st64_b32 v[70:71], v0 offset0:241 offset1:242
	ds_read2st64_b32 v[64:65], v0 offset0:243 offset1:244
	ds_read2st64_b32 v[58:59], v0 offset0:245 offset1:246
	ds_read2st64_b32 v[52:53], v0 offset0:247 offset1:248
	ds_read2st64_b32 v[40:41], v0 offset0:249 offset1:250
	v_lshl_add_u64 v[42:43], v[142:143], 0, s[6:7]
	s_mov_b32 s6, 0x2188000
	s_waitcnt lgkmcnt(14)
	v_pk_add_f32 v[30:31], v[30:31], v[130:131]
	v_add_co_u32_e32 v130, vcc, s6, v142
	v_pk_add_f32 v[30:31], v[30:31], v[132:133]
	s_nop 0
	v_addc_co_u32_e32 v131, vcc, 0, v143, vcc
	global_load_dwordx4 v[130:133], v[130:131], off
	v_pk_add_f32 v[26:27], v[26:27], v[118:119]
	v_pk_add_f32 v[30:31], v[30:31], v[134:135]
	v_pk_add_f32 v[26:27], v[26:27], v[120:121]
	global_load_dwordx4 v[118:121], v[42:43], off offset:64
	v_pk_add_f32 v[22:23], v[22:23], v[106:107]
	v_pk_add_f32 v[32:33], v[32:33], v[122:123]
	v_pk_add_f32 v[22:23], v[22:23], v[108:109]
	global_load_dwordx4 v[106:109], v[42:43], off offset:128
	v_pk_add_f32 v[32:33], v[32:33], v[126:127]
	s_waitcnt lgkmcnt(0)
	v_pk_add_f32 v[26:27], v[26:27], v[124:125]
	v_pk_add_f32 v[32:33], v[32:33], v[128:129]
	v_pk_add_f32 v[28:29], v[28:29], v[110:111]
	v_pk_add_f32 v[22:23], v[22:23], v[112:113]
	v_pk_add_f32 v[28:29], v[28:29], v[114:115]
	v_pk_add_f32 v[24:25], v[24:25], v[98:99]
	v_pk_add_f32 v[28:29], v[28:29], v[116:117]
	v_pk_add_f32 v[24:25], v[24:25], v[102:103]
	v_pk_add_f32 v[18:19], v[18:19], v[92:93]
	v_pk_add_f32 v[24:25], v[24:25], v[104:105]
	v_pk_add_f32 v[18:19], v[18:19], v[96:97]
	v_pk_add_f32 v[20:21], v[20:21], v[86:87]
	v_pk_add_f32 v[18:19], v[18:19], v[100:101]
	v_pk_add_f32 v[20:21], v[20:21], v[90:91]
	v_pk_add_f32 v[14:15], v[14:15], v[80:81]
	v_pk_add_f32 v[20:21], v[20:21], v[94:95]
	v_pk_add_f32 v[14:15], v[14:15], v[84:85]
	v_pk_add_f32 v[16:17], v[16:17], v[74:75]
	v_pk_add_f32 v[14:15], v[14:15], v[88:89]
	v_pk_add_f32 v[16:17], v[16:17], v[78:79]
	v_pk_add_f32 v[10:11], v[10:11], v[68:69]
	v_pk_add_f32 v[16:17], v[16:17], v[82:83]
	v_pk_add_f32 v[10:11], v[10:11], v[72:73]
	v_pk_add_f32 v[12:13], v[12:13], v[62:63]
	v_pk_add_f32 v[10:11], v[10:11], v[76:77]
	v_pk_add_f32 v[12:13], v[12:13], v[66:67]
	v_pk_add_f32 v[6:7], v[6:7], v[56:57]
	v_pk_add_f32 v[12:13], v[12:13], v[70:71]
	v_pk_add_f32 v[6:7], v[6:7], v[60:61]
	v_pk_add_f32 v[2:3], v[2:3], v[44:45]
	v_pk_add_f32 v[6:7], v[6:7], v[64:65]
	v_pk_add_f32 v[8:9], v[8:9], v[50:51]
	v_pk_add_f32 v[2:3], v[2:3], v[48:49]
	v_pk_add_f32 v[8:9], v[8:9], v[54:55]
	v_pk_add_f32 v[2:3], v[2:3], v[52:53]
	v_pk_add_f32 v[8:9], v[8:9], v[58:59]
	v_pk_add_f32 v[4:5], v[4:5], v[36:37]
	s_lshl_b64 s[6:7], s[12:13], 14
	v_pk_add_f32 v[4:5], v[4:5], v[38:39]
	s_and_b32 s16, s22, 1
	v_pk_add_f32 v[4:5], v[4:5], v[40:41]
	s_and_b64 vcc, exec, s[10:11]
	s_waitcnt vmcnt(0)
	v_pk_add_f32 v[30:31], v[30:31], v[130:131]
	s_nop 0
	v_mul_f32_e32 v0, 0x3d372713, v30
	v_mul_f32_e32 v0, v30, v0
	v_fma_f32 v0, v30, v0, v30
	v_mul_f32_e32 v0, 0x3f4c422a, v0
	v_add_f32_e32 v0, v0, v0
	v_mul_f32_e32 v0, 0x3fb8aa3b, v0
	v_exp_f32_e32 v0, v0
	v_pk_add_f32 v[32:33], v[32:33], v[132:133]
	v_pk_add_f32 v[26:27], v[26:27], v[118:119]
	v_pk_add_f32 v[28:29], v[28:29], v[120:121]
	v_add_f32_e32 v0, 1.0, v0
	v_rcp_f32_e32 v130, v0
	v_mul_f32_e32 v0, 0x3d372713, v31
	v_mul_f32_e32 v0, v31, v0
	v_fma_f32 v0, v31, v0, v31
	v_mul_f32_e32 v0, 0x3f4c422a, v0
	v_add_f32_e32 v0, v0, v0
	v_mul_f32_e32 v0, 0x3fb8aa3b, v0
	v_exp_f32_e32 v0, v0
	v_pk_add_f32 v[22:23], v[22:23], v[106:107]
	v_pk_add_f32 v[24:25], v[24:25], v[108:109]
	v_pk_mul_f32 v[30:31], v[30:31], 0.5 op_sel_hi:[1,0]
	v_add_f32_e32 v0, 1.0, v0
	v_rcp_f32_e32 v131, v0
	v_mul_f32_e32 v0, 0x3d372713, v32
	v_mul_f32_e32 v0, v32, v0
	v_fma_f32 v0, v32, v0, v32
	v_mul_f32_e32 v0, 0x3f4c422a, v0
	v_add_f32_e32 v0, v0, v0
	v_mul_f32_e32 v0, 0x3fb8aa3b, v0
	v_exp_f32_e32 v0, v0
	v_pk_fma_f32 v[130:131], v[130:131], 2.0, 1.0 op_sel_hi:[1,0,0] neg_lo:[1,0,0] neg_hi:[1,0,0]
	v_add_f32_e32 v0, 1.0, v0
	v_rcp_f32_e32 v122, v0
	v_mul_f32_e32 v0, 0x3d372713, v33
	v_mul_f32_e32 v0, v33, v0
	v_fma_f32 v0, v33, v0, v33
	v_mul_f32_e32 v0, 0x3f4c422a, v0
	v_add_f32_e32 v0, v0, v0
	v_mul_f32_e32 v0, 0x3fb8aa3b, v0
	v_exp_f32_e32 v0, v0
	v_pk_add_f32 v[130:131], v[130:131], 1.0 op_sel_hi:[1,0]
	v_pk_mul_f32 v[32:33], v[32:33], 0.5 op_sel_hi:[1,0]
	v_pk_mul_f32 v[30:31], v[30:31], v[130:131]
	v_add_f32_e32 v0, 1.0, v0
	v_rcp_f32_e32 v123, v0
	v_mul_f32_e32 v0, 0x3d372713, v26
	v_mul_f32_e32 v0, v26, v0
	v_fma_f32 v0, v26, v0, v26
	v_mul_f32_e32 v0, 0x3f4c422a, v0
	v_add_f32_e32 v0, v0, v0
	v_mul_f32_e32 v0, 0x3fb8aa3b, v0
	v_exp_f32_e32 v0, v0
	v_cvt_pk_bf16_f32 v38, v30, v31
	v_pk_fma_f32 v[122:123], v[122:123], 2.0, 1.0 op_sel_hi:[1,0,0] neg_lo:[1,0,0] neg_hi:[1,0,0]
	v_add_f32_e32 v0, 1.0, v0
	v_rcp_f32_e32 v118, v0
	v_mul_f32_e32 v0, 0x3d372713, v27
	v_mul_f32_e32 v0, v27, v0
	v_fma_f32 v0, v27, v0, v27
	v_mul_f32_e32 v0, 0x3f4c422a, v0
	v_add_f32_e32 v0, v0, v0
	v_mul_f32_e32 v0, 0x3fb8aa3b, v0
	v_exp_f32_e32 v0, v0
	v_pk_mul_f32 v[26:27], v[26:27], 0.5 op_sel_hi:[1,0]
	v_pk_add_f32 v[122:123], v[122:123], 1.0 op_sel_hi:[1,0]
	v_add_f32_e32 v0, 1.0, v0
	v_rcp_f32_e32 v119, v0
	v_mul_f32_e32 v0, 0x3d372713, v28
	v_mul_f32_e32 v0, v28, v0
	v_fma_f32 v0, v28, v0, v28
	v_mul_f32_e32 v0, 0x3f4c422a, v0
	v_add_f32_e32 v0, v0, v0
	v_mul_f32_e32 v0, 0x3fb8aa3b, v0
	v_exp_f32_e32 v0, v0
	v_pk_fma_f32 v[118:119], v[118:119], 2.0, 1.0 op_sel_hi:[1,0,0] neg_lo:[1,0,0] neg_hi:[1,0,0]
	v_pk_mul_f32 v[32:33], v[32:33], v[122:123]
	v_pk_add_f32 v[118:119], v[118:119], 1.0 op_sel_hi:[1,0]
	v_add_f32_e32 v0, 1.0, v0
	v_rcp_f32_e32 v110, v0
	v_mul_f32_e32 v0, 0x3d372713, v29
	v_mul_f32_e32 v0, v29, v0
	v_fma_f32 v0, v29, v0, v29
	v_mul_f32_e32 v0, 0x3f4c422a, v0
	v_add_f32_e32 v0, v0, v0
	v_mul_f32_e32 v0, 0x3fb8aa3b, v0
	v_exp_f32_e32 v0, v0
	v_pk_mul_f32 v[28:29], v[28:29], 0.5 op_sel_hi:[1,0]
	v_pk_mul_f32 v[26:27], v[26:27], v[118:119]
	v_cvt_pk_bf16_f32 v39, v32, v33
	v_add_f32_e32 v0, 1.0, v0
	v_rcp_f32_e32 v111, v0
	v_mul_f32_e32 v0, 0x3d372713, v22
	v_mul_f32_e32 v0, v22, v0
	v_fma_f32 v0, v22, v0, v22
	v_mul_f32_e32 v0, 0x3f4c422a, v0
	v_add_f32_e32 v0, v0, v0
	v_mul_f32_e32 v0, 0x3fb8aa3b, v0
	v_exp_f32_e32 v0, v0
	v_pk_fma_f32 v[110:111], v[110:111], 2.0, 1.0 op_sel_hi:[1,0,0] neg_lo:[1,0,0] neg_hi:[1,0,0]
	v_cvt_pk_bf16_f32 v40, v26, v27
	v_pk_add_f32 v[110:111], v[110:111], 1.0 op_sel_hi:[1,0]
	v_add_f32_e32 v0, 1.0, v0
	v_rcp_f32_e32 v106, v0
	v_mul_f32_e32 v0, 0x3d372713, v23
	v_mul_f32_e32 v0, v23, v0
	v_fma_f32 v0, v23, v0, v23
	v_mul_f32_e32 v0, 0x3f4c422a, v0
	v_add_f32_e32 v0, v0, v0
	v_mul_f32_e32 v0, 0x3fb8aa3b, v0
	v_exp_f32_e32 v0, v0
	v_pk_mul_f32 v[28:29], v[28:29], v[110:111]
	v_pk_mul_f32 v[22:23], v[22:23], 0.5 op_sel_hi:[1,0]
	v_cvt_pk_bf16_f32 v41, v28, v29
	v_add_f32_e32 v0, 1.0, v0
	v_rcp_f32_e32 v107, v0
	v_mul_f32_e32 v0, 0x3d372713, v24
	v_mul_f32_e32 v0, v24, v0
	v_fma_f32 v0, v24, v0, v24
	v_mul_f32_e32 v0, 0x3f4c422a, v0
	v_add_f32_e32 v0, v0, v0
	v_mul_f32_e32 v0, 0x3fb8aa3b, v0
	v_exp_f32_e32 v0, v0
	v_pk_fma_f32 v[106:107], v[106:107], 2.0, 1.0 op_sel_hi:[1,0,0] neg_lo:[1,0,0] neg_hi:[1,0,0]
	v_add_f32_e32 v0, 1.0, v0
	v_rcp_f32_e32 v98, v0
	v_mul_f32_e32 v0, 0x3d372713, v25
	v_mul_f32_e32 v0, v25, v0
	v_fma_f32 v0, v25, v0, v25
	v_mul_f32_e32 v0, 0x3f4c422a, v0
	v_add_f32_e32 v0, v0, v0
	v_mul_f32_e32 v0, 0x3fb8aa3b, v0
	v_exp_f32_e32 v0, v0
	v_pk_mul_f32 v[24:25], v[24:25], 0.5 op_sel_hi:[1,0]
	v_pk_add_f32 v[106:107], v[106:107], 1.0 op_sel_hi:[1,0]
	v_add_f32_e32 v0, 1.0, v0
	v_rcp_f32_e32 v99, v0
	v_pk_mul_f32 v[22:23], v[22:23], v[106:107]
	v_pk_fma_f32 v[98:99], v[98:99], 2.0, 1.0 op_sel_hi:[1,0,0] neg_lo:[1,0,0] neg_hi:[1,0,0]
	s_nop 0
	v_pk_add_f32 v[98:99], v[98:99], 1.0 op_sel_hi:[1,0]
	v_cvt_pk_bf16_f32 v22, v22, v23
	v_pk_mul_f32 v[24:25], v[24:25], v[98:99]
	global_load_dwordx4 v[96:99], v[42:43], off offset:192
	v_cvt_pk_bf16_f32 v23, v24, v25
	s_waitcnt vmcnt(0) lgkmcnt(0)
	v_pk_add_f32 v[18:19], v[18:19], v[96:97]
	s_nop 0
	v_mul_f32_e32 v0, 0x3d372713, v18
	v_mul_f32_e32 v0, v18, v0
	v_fma_f32 v0, v18, v0, v18
	v_mul_f32_e32 v0, 0x3f4c422a, v0
	v_add_f32_e32 v0, v0, v0
	v_mul_f32_e32 v0, 0x3fb8aa3b, v0
	v_exp_f32_e32 v0, v0
	v_pk_add_f32 v[20:21], v[20:21], v[98:99]
	v_add_f32_e32 v0, 1.0, v0
	v_rcp_f32_e32 v92, v0
	v_mul_f32_e32 v0, 0x3d372713, v19
	v_mul_f32_e32 v0, v19, v0
	v_fma_f32 v0, v19, v0, v19
	v_mul_f32_e32 v0, 0x3f4c422a, v0
	v_add_f32_e32 v0, v0, v0
	v_mul_f32_e32 v0, 0x3fb8aa3b, v0
	v_exp_f32_e32 v0, v0
	v_pk_mul_f32 v[18:19], v[18:19], 0.5 op_sel_hi:[1,0]
	v_add_f32_e32 v0, 1.0, v0
	v_rcp_f32_e32 v93, v0
	v_mul_f32_e32 v0, 0x3d372713, v20
	v_mul_f32_e32 v0, v20, v0
	v_fma_f32 v0, v20, v0, v20
	v_mul_f32_e32 v0, 0x3f4c422a, v0
	v_add_f32_e32 v0, v0, v0
	v_mul_f32_e32 v0, 0x3fb8aa3b, v0
	v_exp_f32_e32 v0, v0
	v_pk_fma_f32 v[92:93], v[92:93], 2.0, 1.0 op_sel_hi:[1,0,0] neg_lo:[1,0,0] neg_hi:[1,0,0]
	v_add_f32_e32 v0, 1.0, v0
	v_rcp_f32_e32 v86, v0
	v_mul_f32_e32 v0, 0x3d372713, v21
	v_mul_f32_e32 v0, v21, v0
	v_fma_f32 v0, v21, v0, v21
	v_mul_f32_e32 v0, 0x3f4c422a, v0
	v_add_f32_e32 v0, v0, v0
	v_mul_f32_e32 v0, 0x3fb8aa3b, v0
	v_exp_f32_e32 v0, v0
	v_pk_mul_f32 v[20:21], v[20:21], 0.5 op_sel_hi:[1,0]
	v_pk_add_f32 v[92:93], v[92:93], 1.0 op_sel_hi:[1,0]
	v_add_f32_e32 v0, 1.0, v0
	v_rcp_f32_e32 v87, v0
	v_pk_mul_f32 v[18:19], v[18:19], v[92:93]
	v_pk_fma_f32 v[86:87], v[86:87], 2.0, 1.0 op_sel_hi:[1,0,0] neg_lo:[1,0,0] neg_hi:[1,0,0]
	s_nop 0
	v_pk_add_f32 v[86:87], v[86:87], 1.0 op_sel_hi:[1,0]
	v_cvt_pk_bf16_f32 v24, v18, v19
	v_pk_mul_f32 v[20:21], v[20:21], v[86:87]
	global_load_dwordx4 v[84:87], v[42:43], off offset:256
	v_cvt_pk_bf16_f32 v25, v20, v21
	s_waitcnt vmcnt(0) lgkmcnt(0)
	v_pk_add_f32 v[14:15], v[14:15], v[84:85]
	s_nop 0
	v_mul_f32_e32 v0, 0x3d372713, v14
	v_mul_f32_e32 v0, v14, v0
	v_fma_f32 v0, v14, v0, v14
	v_mul_f32_e32 v0, 0x3f4c422a, v0
	v_add_f32_e32 v0, v0, v0
	v_mul_f32_e32 v0, 0x3fb8aa3b, v0
	v_exp_f32_e32 v0, v0
	v_pk_add_f32 v[16:17], v[16:17], v[86:87]
	v_add_f32_e32 v0, 1.0, v0
	v_rcp_f32_e32 v80, v0
	v_mul_f32_e32 v0, 0x3d372713, v15
	v_mul_f32_e32 v0, v15, v0
	v_fma_f32 v0, v15, v0, v15
	v_mul_f32_e32 v0, 0x3f4c422a, v0
	v_add_f32_e32 v0, v0, v0
	v_mul_f32_e32 v0, 0x3fb8aa3b, v0
	v_exp_f32_e32 v0, v0
	v_pk_mul_f32 v[14:15], v[14:15], 0.5 op_sel_hi:[1,0]
	v_add_f32_e32 v0, 1.0, v0
	v_rcp_f32_e32 v81, v0
	v_mul_f32_e32 v0, 0x3d372713, v16
	v_mul_f32_e32 v0, v16, v0
	v_fma_f32 v0, v16, v0, v16
	v_mul_f32_e32 v0, 0x3f4c422a, v0
	v_add_f32_e32 v0, v0, v0
	v_mul_f32_e32 v0, 0x3fb8aa3b, v0
	v_exp_f32_e32 v0, v0
	v_pk_fma_f32 v[80:81], v[80:81], 2.0, 1.0 op_sel_hi:[1,0,0] neg_lo:[1,0,0] neg_hi:[1,0,0]
	v_add_f32_e32 v0, 1.0, v0
	v_rcp_f32_e32 v74, v0
	v_mul_f32_e32 v0, 0x3d372713, v17
	v_mul_f32_e32 v0, v17, v0
	v_fma_f32 v0, v17, v0, v17
	v_mul_f32_e32 v0, 0x3f4c422a, v0
	v_add_f32_e32 v0, v0, v0
	v_mul_f32_e32 v0, 0x3fb8aa3b, v0
	v_exp_f32_e32 v0, v0
	v_pk_mul_f32 v[16:17], v[16:17], 0.5 op_sel_hi:[1,0]
	v_pk_add_f32 v[80:81], v[80:81], 1.0 op_sel_hi:[1,0]
	v_add_f32_e32 v0, 1.0, v0
	v_rcp_f32_e32 v75, v0
	v_pk_mul_f32 v[14:15], v[14:15], v[80:81]
	v_pk_fma_f32 v[74:75], v[74:75], 2.0, 1.0 op_sel_hi:[1,0,0] neg_lo:[1,0,0] neg_hi:[1,0,0]
	s_nop 0
	v_pk_add_f32 v[74:75], v[74:75], 1.0 op_sel_hi:[1,0]
	v_cvt_pk_bf16_f32 v14, v14, v15
	v_pk_mul_f32 v[16:17], v[16:17], v[74:75]
	global_load_dwordx4 v[72:75], v[42:43], off offset:320
	v_cvt_pk_bf16_f32 v15, v16, v17
	s_waitcnt vmcnt(0) lgkmcnt(0)
	v_pk_add_f32 v[10:11], v[10:11], v[72:73]
	s_nop 0
	v_mul_f32_e32 v0, 0x3d372713, v10
	v_mul_f32_e32 v0, v10, v0
	v_fma_f32 v0, v10, v0, v10
	v_mul_f32_e32 v0, 0x3f4c422a, v0
	v_add_f32_e32 v0, v0, v0
	v_mul_f32_e32 v0, 0x3fb8aa3b, v0
	v_exp_f32_e32 v0, v0
	v_pk_add_f32 v[12:13], v[12:13], v[74:75]
	v_add_f32_e32 v0, 1.0, v0
	v_rcp_f32_e32 v68, v0
	v_mul_f32_e32 v0, 0x3d372713, v11
	v_mul_f32_e32 v0, v11, v0
	v_fma_f32 v0, v11, v0, v11
	v_mul_f32_e32 v0, 0x3f4c422a, v0
	v_add_f32_e32 v0, v0, v0
	v_mul_f32_e32 v0, 0x3fb8aa3b, v0
	v_exp_f32_e32 v0, v0
	v_pk_mul_f32 v[10:11], v[10:11], 0.5 op_sel_hi:[1,0]
	v_add_f32_e32 v0, 1.0, v0
	v_rcp_f32_e32 v69, v0
	v_mul_f32_e32 v0, 0x3d372713, v12
	v_mul_f32_e32 v0, v12, v0
	v_fma_f32 v0, v12, v0, v12
	v_mul_f32_e32 v0, 0x3f4c422a, v0
	v_add_f32_e32 v0, v0, v0
	v_mul_f32_e32 v0, 0x3fb8aa3b, v0
	v_exp_f32_e32 v0, v0
	v_pk_fma_f32 v[68:69], v[68:69], 2.0, 1.0 op_sel_hi:[1,0,0] neg_lo:[1,0,0] neg_hi:[1,0,0]
	v_add_f32_e32 v0, 1.0, v0
	v_rcp_f32_e32 v62, v0
	v_mul_f32_e32 v0, 0x3d372713, v13
	v_mul_f32_e32 v0, v13, v0
	v_fma_f32 v0, v13, v0, v13
	v_mul_f32_e32 v0, 0x3f4c422a, v0
	v_add_f32_e32 v0, v0, v0
	v_mul_f32_e32 v0, 0x3fb8aa3b, v0
	v_exp_f32_e32 v0, v0
	v_pk_mul_f32 v[12:13], v[12:13], 0.5 op_sel_hi:[1,0]
	v_pk_add_f32 v[68:69], v[68:69], 1.0 op_sel_hi:[1,0]
	v_add_f32_e32 v0, 1.0, v0
	v_rcp_f32_e32 v63, v0
	v_pk_mul_f32 v[10:11], v[10:11], v[68:69]
	v_pk_fma_f32 v[62:63], v[62:63], 2.0, 1.0 op_sel_hi:[1,0,0] neg_lo:[1,0,0] neg_hi:[1,0,0]
	s_nop 0
	v_pk_add_f32 v[62:63], v[62:63], 1.0 op_sel_hi:[1,0]
	v_cvt_pk_bf16_f32 v16, v10, v11
	v_pk_mul_f32 v[12:13], v[12:13], v[62:63]
	global_load_dwordx4 v[60:63], v[42:43], off offset:384
	v_cvt_pk_bf16_f32 v17, v12, v13
	global_load_dwordx4 v[42:45], v[42:43], off offset:448
	s_waitcnt vmcnt(0) lgkmcnt(0)
	v_pk_add_f32 v[6:7], v[6:7], v[60:61]
	s_nop 0
	v_mul_f32_e32 v0, 0x3d372713, v6
	v_mul_f32_e32 v0, v6, v0
	v_fma_f32 v0, v6, v0, v6
	v_mul_f32_e32 v0, 0x3f4c422a, v0
	v_add_f32_e32 v0, v0, v0
	v_mul_f32_e32 v0, 0x3fb8aa3b, v0
	v_exp_f32_e32 v0, v0
	v_pk_add_f32 v[8:9], v[8:9], v[62:63]
	v_pk_add_f32 v[2:3], v[2:3], v[42:43]
	v_pk_add_f32 v[4:5], v[4:5], v[44:45]
	v_add_f32_e32 v0, 1.0, v0
	v_rcp_f32_e32 v56, v0
	v_mul_f32_e32 v0, 0x3d372713, v7
	v_mul_f32_e32 v0, v7, v0
	v_fma_f32 v0, v7, v0, v7
	v_mul_f32_e32 v0, 0x3f4c422a, v0
	v_add_f32_e32 v0, v0, v0
	v_mul_f32_e32 v0, 0x3fb8aa3b, v0
	v_exp_f32_e32 v0, v0
	v_pk_mul_f32 v[6:7], v[6:7], 0.5 op_sel_hi:[1,0]
	v_add_f32_e32 v0, 1.0, v0
	v_rcp_f32_e32 v57, v0
	v_mul_f32_e32 v0, 0x3d372713, v8
	v_mul_f32_e32 v0, v8, v0
	v_fma_f32 v0, v8, v0, v8
	v_mul_f32_e32 v0, 0x3f4c422a, v0
	v_add_f32_e32 v0, v0, v0
	v_mul_f32_e32 v0, 0x3fb8aa3b, v0
	v_exp_f32_e32 v0, v0
	v_pk_fma_f32 v[56:57], v[56:57], 2.0, 1.0 op_sel_hi:[1,0,0] neg_lo:[1,0,0] neg_hi:[1,0,0]
	v_add_f32_e32 v0, 1.0, v0
	v_rcp_f32_e32 v50, v0
	v_mul_f32_e32 v0, 0x3d372713, v9
	v_mul_f32_e32 v0, v9, v0
	v_fma_f32 v0, v9, v0, v9
	v_mul_f32_e32 v0, 0x3f4c422a, v0
	v_add_f32_e32 v0, v0, v0
	v_mul_f32_e32 v0, 0x3fb8aa3b, v0
	v_exp_f32_e32 v0, v0
	v_pk_add_f32 v[56:57], v[56:57], 1.0 op_sel_hi:[1,0]
	v_pk_mul_f32 v[8:9], v[8:9], 0.5 op_sel_hi:[1,0]
	v_pk_mul_f32 v[6:7], v[6:7], v[56:57]
	v_add_f32_e32 v0, 1.0, v0
	v_rcp_f32_e32 v51, v0
	v_mul_f32_e32 v0, 0x3d372713, v2
	v_mul_f32_e32 v0, v2, v0
	v_fma_f32 v0, v2, v0, v2
	v_mul_f32_e32 v0, 0x3f4c422a, v0
	v_add_f32_e32 v0, v0, v0
	v_mul_f32_e32 v0, 0x3fb8aa3b, v0
	v_exp_f32_e32 v0, v0
	v_pk_fma_f32 v[50:51], v[50:51], 2.0, 1.0 op_sel_hi:[1,0,0] neg_lo:[1,0,0] neg_hi:[1,0,0]
	v_add_f32_e32 v0, 1.0, v0
	v_rcp_f32_e32 v42, v0
	v_mul_f32_e32 v0, 0x3d372713, v3
	v_mul_f32_e32 v0, v3, v0
	v_fma_f32 v0, v3, v0, v3
	v_mul_f32_e32 v0, 0x3f4c422a, v0
	v_add_f32_e32 v0, v0, v0
	v_mul_f32_e32 v0, 0x3fb8aa3b, v0
	v_exp_f32_e32 v0, v0
	v_pk_mul_f32 v[2:3], v[2:3], 0.5 op_sel_hi:[1,0]
	v_pk_add_f32 v[50:51], v[50:51], 1.0 op_sel_hi:[1,0]
	v_add_f32_e32 v0, 1.0, v0
	v_rcp_f32_e32 v43, v0
	v_mul_f32_e32 v0, 0x3d372713, v4
	v_mul_f32_e32 v0, v4, v0
	v_fma_f32 v0, v4, v0, v4
	v_mul_f32_e32 v0, 0x3f4c422a, v0
	v_add_f32_e32 v0, v0, v0
	v_mul_f32_e32 v0, 0x3fb8aa3b, v0
	v_exp_f32_e32 v0, v0
	v_pk_fma_f32 v[42:43], v[42:43], 2.0, 1.0 op_sel_hi:[1,0,0] neg_lo:[1,0,0] neg_hi:[1,0,0]
	v_pk_mul_f32 v[8:9], v[8:9], v[50:51]
	v_pk_add_f32 v[42:43], v[42:43], 1.0 op_sel_hi:[1,0]
	v_add_f32_e32 v0, 1.0, v0
	v_rcp_f32_e32 v36, v0
	v_mul_f32_e32 v0, 0x3d372713, v5
	v_mul_f32_e32 v0, v5, v0
	v_fma_f32 v0, v5, v0, v5
	v_mul_f32_e32 v0, 0x3f4c422a, v0
	v_add_f32_e32 v0, v0, v0
	v_mul_f32_e32 v0, 0x3fb8aa3b, v0
	v_exp_f32_e32 v0, v0
	v_pk_mul_f32 v[4:5], v[4:5], 0.5 op_sel_hi:[1,0]
	v_pk_mul_f32 v[2:3], v[2:3], v[42:43]
	v_add_f32_e32 v0, 1.0, v0
	v_rcp_f32_e32 v37, v0
	v_lshlrev_b32_e32 v0, 8, v140
	v_pk_fma_f32 v[36:37], v[36:37], 2.0, 1.0 op_sel_hi:[1,0,0] neg_lo:[1,0,0] neg_hi:[1,0,0]
	s_nop 0
	v_pk_add_f32 v[36:37], v[36:37], 1.0 op_sel_hi:[1,0]
	s_nop 0
	v_pk_mul_f32 v[4:5], v[4:5], v[36:37]
	v_lshl_add_u64 v[36:37], v[46:47], 0, s[6:7]
	v_lshl_add_u64 v[36:37], v[34:35], 1, v[36:37]
	s_mov_b64 s[6:7], 0x2180000
	v_lshl_add_u64 v[56:57], v[36:37], 0, s[6:7]
	v_lshl_add_u64 v[30:31], v[56:57], 0, v[0:1]
	v_mov_b32_e32 v219, v1
	v_or_b32_e32 v218, 0x1000, v0
	v_lshl_add_u64 v[212:213], v[56:57], 0, v[218:219]
	v_or_b32_e32 v218, 0x2000, v0
	v_lshl_add_u64 v[214:215], v[56:57], 0, v[218:219]
	v_or_b32_e32 v218, 0x3000, v0
	v_lshl_add_u64 v[216:217], v[56:57], 0, v[218:219]
	global_load_dwordx2 v[144:145], v[30:31], off
	global_load_dwordx2 v[146:147], v[30:31], off offset:32
	global_load_dwordx2 v[148:149], v[30:31], off offset:64
	global_load_dwordx2 v[150:151], v[30:31], off offset:96
	global_load_dwordx2 v[152:153], v[30:31], off offset:128
	global_load_dwordx2 v[154:155], v[30:31], off offset:160
	global_load_dwordx2 v[156:157], v[30:31], off offset:192
	global_load_dwordx2 v[158:159], v[30:31], off offset:224
	global_load_dwordx2 v[160:161], v[212:213], off
	global_load_dwordx2 v[162:163], v[212:213], off offset:32
	global_load_dwordx2 v[164:165], v[212:213], off offset:64
	global_load_dwordx2 v[166:167], v[212:213], off offset:96
	global_load_dwordx2 v[168:169], v[212:213], off offset:128
	global_load_dwordx2 v[170:171], v[212:213], off offset:160
	global_load_dwordx2 v[172:173], v[212:213], off offset:192
	global_load_dwordx2 v[174:175], v[212:213], off offset:224
	global_load_dwordx2 v[176:177], v[214:215], off
	global_load_dwordx2 v[178:179], v[214:215], off offset:32
	global_load_dwordx2 v[180:181], v[214:215], off offset:64
	global_load_dwordx2 v[182:183], v[214:215], off offset:96
	global_load_dwordx2 v[184:185], v[214:215], off offset:128
	global_load_dwordx2 v[186:187], v[214:215], off offset:160
	global_load_dwordx2 v[188:189], v[214:215], off offset:192
	global_load_dwordx2 v[190:191], v[214:215], off offset:224
	global_load_dwordx2 v[192:193], v[216:217], off
	global_load_dwordx2 v[194:195], v[216:217], off offset:32
	global_load_dwordx2 v[200:201], v[216:217], off offset:64
	global_load_dwordx2 v[202:203], v[216:217], off offset:96
	global_load_dwordx2 v[204:205], v[216:217], off offset:128
	global_load_dwordx2 v[206:207], v[216:217], off offset:160
	global_load_dwordx2 v[208:209], v[216:217], off offset:192
	global_load_dwordx2 v[210:211], v[216:217], off offset:224
	s_waitcnt vmcnt(0) lgkmcnt(0)
	v_mfma_f32_16x16x32_bf16 v[42:45], v[144:147], v[38:41], 0
	v_mfma_f32_16x16x32_bf16 v[48:51], v[160:163], v[38:41], 0
	v_mfma_f32_16x16x32_bf16 v[18:21], v[148:151], v[22:25], v[42:45]
	v_mfma_f32_16x16x32_bf16 v[52:55], v[176:179], v[38:41], 0
	v_mfma_f32_16x16x32_bf16 v[38:41], v[192:195], v[38:41], 0
	v_mfma_f32_16x16x32_bf16 v[42:45], v[164:167], v[22:25], v[48:51]
	v_mfma_f32_16x16x32_bf16 v[48:51], v[180:183], v[22:25], v[52:55]
	v_mfma_f32_16x16x32_bf16 v[22:25], v[200:203], v[22:25], v[38:41]
	v_mfma_f32_16x16x32_bf16 v[38:41], v[152:155], v[14:17], v[18:21]
	v_mfma_f32_16x16x32_bf16 v[42:45], v[168:171], v[14:17], v[42:45]
	v_mfma_f32_16x16x32_bf16 v[18:21], v[184:187], v[14:17], v[48:51]
	v_mfma_f32_16x16x32_bf16 v[10:13], v[204:207], v[14:17], v[22:25]
	s_nop 7
	v_cvt_pk_bf16_f32 v15, v8, v9
	v_cvt_pk_bf16_f32 v14, v6, v7
	v_cvt_pk_bf16_f32 v16, v2, v3
	v_cvt_pk_bf16_f32 v17, v4, v5
	s_mov_b64 s[6:7], -1
	s_nop 1
	v_mfma_f32_16x16x32_bf16 v[2:5], v[156:159], v[14:17], v[38:41]
	v_mfma_f32_16x16x32_bf16 v[18:21], v[188:191], v[14:17], v[18:21]
	v_mfma_f32_16x16x32_bf16 v[6:9], v[172:175], v[14:17], v[42:45]
	v_mfma_f32_16x16x32_bf16 v[10:13], v[208:211], v[14:17], v[10:13]
	s_cbranch_vccz .LBB0_313
	s_lshl_b32 s6, s21, 16
	s_lshl_b32 s7, s16, 15
	v_lshlrev_b32_e32 v16, 1, v140
	v_lshrrev_b32_e32 v17, 1, v139
	s_or_b32 s74, s7, s6
	v_and_b32_e32 v0, 3, v139
	v_and_b32_e32 v16, 8, v16
	v_and_b32_e32 v17, 4, v17
	v_lshl_add_u64 v[14:15], v[46:47], 0, s[74:75]
	s_lshl_b32 s74, s20, 11
	v_or3_b32 v0, v17, v0, v16
	v_lshl_add_u64 v[14:15], v[14:15], 0, s[74:75]
	v_lshlrev_b32_e32 v0, 1, v0
	v_lshl_add_u64 v[14:15], v[14:15], 0, v[0:1]
	s_mov_b64 s[6:7], 0x2309000
	v_lshlrev_b32_e32 v16, 6, v138
	v_lshl_add_u64 v[14:15], v[14:15], 0, s[6:7]
	v_cvt_pk_bf16_f32 v0, v2, s0
	v_ashrrev_i32_e32 v17, 31, v16
	v_cndmask_b32_e64 v0, v0, 0, s[8:9]
	v_lshl_add_u64 v[16:17], v[16:17], 1, v[14:15]
	v_lshlrev_b32_e32 v24, 4, v34
	global_store_short v[16:17], v0, off
	v_cvt_pk_bf16_f32 v0, v3, s0
	v_cndmask_b32_e64 v0, v0, 0, s[8:9]
	v_or_b32_e32 v22, 32, v24
	global_store_short v[16:17], v0, off offset:32
	v_cvt_pk_bf16_f32 v0, v4, s0
	v_ashrrev_i32_e32 v23, 31, v22
	v_cndmask_b32_e64 v0, v0, 0, s[8:9]
	v_lshl_add_u64 v[22:23], v[22:23], 1, v[14:15]
	global_store_short v[22:23], v0, off
	v_cvt_pk_bf16_f32 v0, v5, s0
	v_cndmask_b32_e64 v0, v0, 0, s[8:9]
	v_add_u32_e32 v22, 0x100, v24
	global_store_short v[16:17], v0, off offset:96
	v_cvt_pk_bf16_f32 v0, v6, s0
	v_ashrrev_i32_e32 v23, 31, v22
	v_cndmask_b32_e64 v0, v0, 0, s[8:9]
	v_lshl_add_u64 v[22:23], v[22:23], 1, v[14:15]
	global_store_short v[22:23], v0, off
	v_cvt_pk_bf16_f32 v0, v7, s0
	v_cndmask_b32_e64 v0, v0, 0, s[8:9]
	v_add_u32_e32 v22, 0x120, v24
	global_store_short v[16:17], v0, off offset:544
	v_cvt_pk_bf16_f32 v0, v8, s0
	v_ashrrev_i32_e32 v23, 31, v22
	v_cndmask_b32_e64 v0, v0, 0, s[8:9]
	v_lshl_add_u64 v[22:23], v[22:23], 1, v[14:15]
	global_store_short v[22:23], v0, off
	v_cvt_pk_bf16_f32 v0, v9, s0
	v_cndmask_b32_e64 v0, v0, 0, s[8:9]
	v_add_u32_e32 v22, 0x200, v24
	global_store_short v[16:17], v0, off offset:608
	v_cvt_pk_bf16_f32 v0, v18, s0
	v_ashrrev_i32_e32 v23, 31, v22
	v_cndmask_b32_e64 v0, v0, 0, s[8:9]
	v_lshl_add_u64 v[22:23], v[22:23], 1, v[14:15]
	global_store_short v[22:23], v0, off
	v_cvt_pk_bf16_f32 v0, v19, s0
	v_cndmask_b32_e64 v0, v0, 0, s[8:9]
	v_add_u32_e32 v22, 0x220, v24
	global_store_short v[16:17], v0, off offset:1056
	v_cvt_pk_bf16_f32 v0, v20, s0
	v_ashrrev_i32_e32 v23, 31, v22
	v_cndmask_b32_e64 v0, v0, 0, s[8:9]
	v_lshl_add_u64 v[22:23], v[22:23], 1, v[14:15]
	global_store_short v[22:23], v0, off
	v_cvt_pk_bf16_f32 v0, v21, s0
	v_cndmask_b32_e64 v0, v0, 0, s[8:9]
	v_add_u32_e32 v22, 0x300, v24
	global_store_short v[16:17], v0, off offset:1120
	v_cvt_pk_bf16_f32 v0, v10, s0
	v_ashrrev_i32_e32 v23, 31, v22
	v_cndmask_b32_e64 v0, v0, 0, s[8:9]
	v_lshl_add_u64 v[22:23], v[22:23], 1, v[14:15]
	global_store_short v[22:23], v0, off
	v_cvt_pk_bf16_f32 v0, v11, s0
	v_cndmask_b32_e64 v0, v0, 0, s[8:9]
	v_add_u32_e32 v22, 0x320, v24
	global_store_short v[16:17], v0, off offset:1568
	v_cvt_pk_bf16_f32 v0, v12, s0
	v_ashrrev_i32_e32 v23, 31, v22
	v_cndmask_b32_e64 v0, v0, 0, s[8:9]
	v_lshl_add_u64 v[14:15], v[22:23], 1, v[14:15]
	global_store_short v[14:15], v0, off
	v_cvt_pk_bf16_f32 v0, v13, s0
	v_cndmask_b32_e64 v0, v0, 0, s[8:9]
	global_store_short v[16:17], v0, off offset:1632
	s_mov_b64 s[6:7], 0
